# barrier leader skips the L2 write-back after phases whose stores are all write-through (3,7,13,19 and, with sc1 row-sum partials, the EpiRes phases)
# baseline (speedup 1.0000x reference)
.LBB0_622:
	s_lshl_b32 s66, s48, 2
	v_cndmask_b32_e64 v144, 0, 1, s[20:21]
	v_cmp_ne_u32_e64 s[12:13], 1, v144
	s_andn2_b64 vcc, exec, s[20:21]
	s_ashr_i32 s67, s66, 31
	s_cbranch_vccnz .LBB0_626
	v_mul_f32_e32 v124, v124, v124
	v_mul_f32_e32 v120, v120, v120
	v_mul_f32_e32 v112, v112, v112
	v_fmac_f32_e32 v124, v125, v125
	v_fmac_f32_e32 v120, v121, v121
	v_mul_f32_e32 v116, v116, v116
	v_fmac_f32_e32 v112, v113, v113
	v_fmac_f32_e32 v124, v126, v126
	v_fmac_f32_e32 v120, v122, v122
	v_fmac_f32_e32 v116, v117, v117
	v_fmac_f32_e32 v112, v114, v114
	v_and_b32_e32 v114, 64, v197
	v_fmac_f32_e32 v124, v127, v127
	v_fmac_f32_e32 v120, v123, v123
	v_fmac_f32_e32 v116, v118, v118
	v_xor_b32_e32 v113, 16, v197
	v_add_u32_e32 v114, 64, v114
	v_add_f32_e32 v120, v124, v120
	v_fmac_f32_e32 v116, v119, v119
	v_cmp_lt_i32_e32 vcc, v113, v114
	v_add_f32_e32 v116, v120, v116
	v_fmac_f32_e32 v112, v115, v115
	v_cndmask_b32_e32 v113, v197, v113, vcc
	v_add_f32_e32 v112, v116, v112
	v_lshlrev_b32_e32 v113, 2, v113
	ds_bpermute_b32 v113, v113, v112
	s_waitcnt lgkmcnt(0)
	v_add_f32_e32 v112, v112, v113
	v_xor_b32_e32 v113, 32, v197
	v_cmp_lt_i32_e32 vcc, v113, v114
	s_nop 1
	v_cndmask_b32_e32 v113, v197, v113, vcc
	v_lshlrev_b32_e32 v113, 2, v113
	ds_bpermute_b32 v113, v113, v112
	s_and_saveexec_b64 s[72:73], s[6:7]
	s_cbranch_execz .LBB0_625
	v_lshlrev_b64 v[114:115], 6, v[142:143]
	v_lshl_add_u64 v[114:115], s[94:95], 0, v[114:115]
	v_lshl_add_u64 v[114:115], s[66:67], 2, v[114:115]
	s_lshl_b32 s48, s87, 2
	v_lshl_add_u64 v[114:115], v[114:115], 0, s[48:49]
	s_waitcnt lgkmcnt(0)
	v_add_f32_e32 v112, v112, v113
	global_store_dword v[114:115], v112, off sc1

.LBB0_643:
	v_mul_f32_e32 v108, v108, v108
	v_mul_f32_e32 v104, v104, v104
	v_mul_f32_e32 v96, v96, v96
	v_fmac_f32_e32 v108, v109, v109
	v_fmac_f32_e32 v104, v105, v105
	v_mul_f32_e32 v100, v100, v100
	v_fmac_f32_e32 v96, v97, v97
	v_fmac_f32_e32 v108, v110, v110
	v_fmac_f32_e32 v104, v106, v106
	v_fmac_f32_e32 v100, v101, v101
	v_fmac_f32_e32 v96, v98, v98
	v_and_b32_e32 v98, 64, v197
	v_fmac_f32_e32 v108, v111, v111
	v_fmac_f32_e32 v104, v107, v107
	v_fmac_f32_e32 v100, v102, v102
	v_xor_b32_e32 v97, 16, v197
	v_add_u32_e32 v98, 64, v98
	v_add_f32_e32 v104, v108, v104
	v_fmac_f32_e32 v100, v103, v103
	v_cmp_lt_i32_e32 vcc, v97, v98
	v_add_f32_e32 v100, v104, v100
	v_fmac_f32_e32 v96, v99, v99
	v_cndmask_b32_e32 v97, v197, v97, vcc
	v_add_f32_e32 v96, v100, v96
	v_lshlrev_b32_e32 v97, 2, v97
	ds_bpermute_b32 v97, v97, v96
	s_waitcnt lgkmcnt(0)
	v_add_f32_e32 v96, v96, v97
	v_xor_b32_e32 v97, 32, v197
	v_cmp_lt_i32_e32 vcc, v97, v98
	s_nop 1
	v_cndmask_b32_e32 v97, v197, v97, vcc
	v_lshlrev_b32_e32 v97, 2, v97
	ds_bpermute_b32 v97, v97, v96
	s_and_saveexec_b64 s[72:73], s[6:7]
	s_cbranch_execz .LBB0_645
	v_lshlrev_b64 v[98:99], 6, v[112:113]
	v_lshl_add_u64 v[98:99], s[94:95], 0, v[98:99]
	v_lshl_add_u64 v[98:99], s[66:67], 2, v[98:99]
	s_lshl_b32 s48, s87, 2
	v_lshl_add_u64 v[98:99], v[98:99], 0, s[48:49]
	s_waitcnt lgkmcnt(0)
	v_add_f32_e32 v96, v96, v97
	global_store_dword v[98:99], v96, off sc1

.LBB0_663:
	v_mul_f32_e32 v92, v92, v92
	v_mul_f32_e32 v88, v88, v88
	v_mul_f32_e32 v80, v80, v80
	v_fmac_f32_e32 v92, v93, v93
	v_fmac_f32_e32 v88, v89, v89
	v_mul_f32_e32 v84, v84, v84
	v_fmac_f32_e32 v80, v81, v81
	v_fmac_f32_e32 v92, v94, v94
	v_fmac_f32_e32 v88, v90, v90
	v_fmac_f32_e32 v84, v85, v85
	v_fmac_f32_e32 v80, v82, v82
	v_and_b32_e32 v82, 64, v197
	v_fmac_f32_e32 v92, v95, v95
	v_fmac_f32_e32 v88, v91, v91
	v_fmac_f32_e32 v84, v86, v86
	v_xor_b32_e32 v81, 16, v197
	v_add_u32_e32 v82, 64, v82
	v_add_f32_e32 v88, v92, v88
	v_fmac_f32_e32 v84, v87, v87
	v_cmp_lt_i32_e32 vcc, v81, v82
	v_add_f32_e32 v84, v88, v84
	v_fmac_f32_e32 v80, v83, v83
	v_cndmask_b32_e32 v81, v197, v81, vcc
	v_add_f32_e32 v80, v84, v80
	v_lshlrev_b32_e32 v81, 2, v81
	ds_bpermute_b32 v81, v81, v80
	s_waitcnt lgkmcnt(0)
	v_add_f32_e32 v80, v80, v81
	v_xor_b32_e32 v81, 32, v197
	v_cmp_lt_i32_e32 vcc, v81, v82
	s_nop 1
	v_cndmask_b32_e32 v81, v197, v81, vcc
	v_lshlrev_b32_e32 v81, 2, v81
	ds_bpermute_b32 v81, v81, v80
	s_and_saveexec_b64 s[72:73], s[6:7]
	s_cbranch_execz .LBB0_665
	v_lshlrev_b64 v[82:83], 6, v[96:97]
	v_lshl_add_u64 v[82:83], s[94:95], 0, v[82:83]
	v_lshl_add_u64 v[82:83], s[66:67], 2, v[82:83]
	s_lshl_b32 s48, s87, 2
	v_lshl_add_u64 v[82:83], v[82:83], 0, s[48:49]
	s_waitcnt lgkmcnt(0)
	v_add_f32_e32 v80, v80, v81
	global_store_dword v[82:83], v80, off sc1

.LBB0_683:
	v_mul_f32_e32 v76, v76, v76
	v_mul_f32_e32 v72, v72, v72
	v_mul_f32_e32 v64, v64, v64
	v_fmac_f32_e32 v76, v77, v77
	v_fmac_f32_e32 v72, v73, v73
	v_mul_f32_e32 v68, v68, v68
	v_fmac_f32_e32 v64, v65, v65
	v_fmac_f32_e32 v76, v78, v78
	v_fmac_f32_e32 v72, v74, v74
	v_fmac_f32_e32 v68, v69, v69
	v_fmac_f32_e32 v64, v66, v66
	v_and_b32_e32 v66, 64, v197
	v_fmac_f32_e32 v76, v79, v79
	v_fmac_f32_e32 v72, v75, v75
	v_fmac_f32_e32 v68, v70, v70
	v_xor_b32_e32 v65, 16, v197
	v_add_u32_e32 v66, 64, v66
	v_add_f32_e32 v72, v76, v72
	v_fmac_f32_e32 v68, v71, v71
	v_cmp_lt_i32_e32 vcc, v65, v66
	v_add_f32_e32 v68, v72, v68
	v_fmac_f32_e32 v64, v67, v67
	v_cndmask_b32_e32 v65, v197, v65, vcc
	v_add_f32_e32 v64, v68, v64
	v_lshlrev_b32_e32 v65, 2, v65
	ds_bpermute_b32 v65, v65, v64
	s_waitcnt lgkmcnt(0)
	v_add_f32_e32 v64, v64, v65
	v_xor_b32_e32 v65, 32, v197
	v_cmp_lt_i32_e32 vcc, v65, v66
	s_nop 1
	v_cndmask_b32_e32 v65, v197, v65, vcc
	v_lshlrev_b32_e32 v65, 2, v65
	ds_bpermute_b32 v65, v65, v64
	s_and_saveexec_b64 s[72:73], s[6:7]
	s_cbranch_execz .LBB0_685
	v_lshlrev_b64 v[66:67], 6, v[80:81]
	v_lshl_add_u64 v[66:67], s[94:95], 0, v[66:67]
	v_lshl_add_u64 v[66:67], s[66:67], 2, v[66:67]
	s_lshl_b32 s48, s87, 2
	v_lshl_add_u64 v[66:67], v[66:67], 0, s[48:49]
	s_waitcnt lgkmcnt(0)
	v_add_f32_e32 v64, v64, v65
	global_store_dword v[66:67], v64, off sc1

.LBB0_703:
	v_mul_f32_e32 v60, v60, v60
	v_mul_f32_e32 v56, v56, v56
	v_mul_f32_e32 v48, v48, v48
	v_fmac_f32_e32 v60, v61, v61
	v_fmac_f32_e32 v56, v57, v57
	v_mul_f32_e32 v52, v52, v52
	v_fmac_f32_e32 v48, v49, v49
	v_fmac_f32_e32 v60, v62, v62
	v_fmac_f32_e32 v56, v58, v58
	v_fmac_f32_e32 v52, v53, v53
	v_fmac_f32_e32 v48, v50, v50
	v_and_b32_e32 v50, 64, v197
	v_fmac_f32_e32 v60, v63, v63
	v_fmac_f32_e32 v56, v59, v59
	v_fmac_f32_e32 v52, v54, v54
	v_xor_b32_e32 v49, 16, v197
	v_add_u32_e32 v50, 64, v50
	v_add_f32_e32 v56, v60, v56
	v_fmac_f32_e32 v52, v55, v55
	v_cmp_lt_i32_e32 vcc, v49, v50
	v_add_f32_e32 v52, v56, v52
	v_fmac_f32_e32 v48, v51, v51
	v_cndmask_b32_e32 v49, v197, v49, vcc
	v_add_f32_e32 v48, v52, v48
	v_lshlrev_b32_e32 v49, 2, v49
	ds_bpermute_b32 v49, v49, v48
	s_waitcnt lgkmcnt(0)
	v_add_f32_e32 v48, v48, v49
	v_xor_b32_e32 v49, 32, v197
	v_cmp_lt_i32_e32 vcc, v49, v50
	s_nop 1
	v_cndmask_b32_e32 v49, v197, v49, vcc
	v_lshlrev_b32_e32 v49, 2, v49
	ds_bpermute_b32 v49, v49, v48
	s_and_saveexec_b64 s[72:73], s[6:7]
	s_cbranch_execz .LBB0_705
	v_lshlrev_b64 v[50:51], 6, v[64:65]
	v_lshl_add_u64 v[50:51], s[94:95], 0, v[50:51]
	v_lshl_add_u64 v[50:51], s[66:67], 2, v[50:51]
	s_lshl_b32 s48, s87, 2
	v_lshl_add_u64 v[50:51], v[50:51], 0, s[48:49]
	s_waitcnt lgkmcnt(0)
	v_add_f32_e32 v48, v48, v49
	global_store_dword v[50:51], v48, off sc1

.LBB0_723:
	v_mul_f32_e32 v44, v44, v44
	v_mul_f32_e32 v40, v40, v40
	v_mul_f32_e32 v32, v32, v32
	v_fmac_f32_e32 v44, v45, v45
	v_fmac_f32_e32 v40, v41, v41
	v_mul_f32_e32 v36, v36, v36
	v_fmac_f32_e32 v32, v33, v33
	v_fmac_f32_e32 v44, v46, v46
	v_fmac_f32_e32 v40, v42, v42
	v_fmac_f32_e32 v36, v37, v37
	v_fmac_f32_e32 v32, v34, v34
	v_and_b32_e32 v34, 64, v197
	v_fmac_f32_e32 v44, v47, v47
	v_fmac_f32_e32 v40, v43, v43
	v_fmac_f32_e32 v36, v38, v38
	v_xor_b32_e32 v33, 16, v197
	v_add_u32_e32 v34, 64, v34
	v_add_f32_e32 v40, v44, v40
	v_fmac_f32_e32 v36, v39, v39
	v_cmp_lt_i32_e32 vcc, v33, v34
	v_add_f32_e32 v36, v40, v36
	v_fmac_f32_e32 v32, v35, v35
	v_cndmask_b32_e32 v33, v197, v33, vcc
	v_add_f32_e32 v32, v36, v32
	v_lshlrev_b32_e32 v33, 2, v33
	ds_bpermute_b32 v33, v33, v32
	s_waitcnt lgkmcnt(0)
	v_add_f32_e32 v32, v32, v33
	v_xor_b32_e32 v33, 32, v197
	v_cmp_lt_i32_e32 vcc, v33, v34
	s_nop 1
	v_cndmask_b32_e32 v33, v197, v33, vcc
	v_lshlrev_b32_e32 v33, 2, v33
	ds_bpermute_b32 v33, v33, v32
	s_and_saveexec_b64 s[72:73], s[6:7]
	s_cbranch_execz .LBB0_725
	v_lshlrev_b64 v[34:35], 6, v[48:49]
	v_lshl_add_u64 v[34:35], s[94:95], 0, v[34:35]
	v_lshl_add_u64 v[34:35], s[66:67], 2, v[34:35]
	s_lshl_b32 s48, s87, 2
	v_lshl_add_u64 v[34:35], v[34:35], 0, s[48:49]
	s_waitcnt lgkmcnt(0)
	v_add_f32_e32 v32, v32, v33
	global_store_dword v[34:35], v32, off sc1

.LBB0_743:
	v_mul_f32_e32 v28, v28, v28
	v_mul_f32_e32 v24, v24, v24
	v_mul_f32_e32 v16, v16, v16
	v_fmac_f32_e32 v28, v29, v29
	v_fmac_f32_e32 v24, v25, v25
	v_mul_f32_e32 v20, v20, v20
	v_fmac_f32_e32 v16, v17, v17
	v_fmac_f32_e32 v28, v30, v30
	v_fmac_f32_e32 v24, v26, v26
	v_fmac_f32_e32 v20, v21, v21
	v_fmac_f32_e32 v16, v18, v18
	v_and_b32_e32 v18, 64, v197
	v_fmac_f32_e32 v28, v31, v31
	v_fmac_f32_e32 v24, v27, v27
	v_fmac_f32_e32 v20, v22, v22
	v_xor_b32_e32 v17, 16, v197
	v_add_u32_e32 v18, 64, v18
	v_add_f32_e32 v24, v28, v24
	v_fmac_f32_e32 v20, v23, v23
	v_cmp_lt_i32_e32 vcc, v17, v18
	v_add_f32_e32 v20, v24, v20
	v_fmac_f32_e32 v16, v19, v19
	v_cndmask_b32_e32 v17, v197, v17, vcc
	v_add_f32_e32 v16, v20, v16
	v_lshlrev_b32_e32 v17, 2, v17
	ds_bpermute_b32 v17, v17, v16
	s_waitcnt lgkmcnt(0)
	v_add_f32_e32 v16, v16, v17
	v_xor_b32_e32 v17, 32, v197
	v_cmp_lt_i32_e32 vcc, v17, v18
	s_nop 1
	v_cndmask_b32_e32 v17, v197, v17, vcc
	v_lshlrev_b32_e32 v17, 2, v17
	ds_bpermute_b32 v17, v17, v16
	s_and_saveexec_b64 s[72:73], s[6:7]
	s_cbranch_execz .LBB0_745
	v_lshlrev_b64 v[18:19], 6, v[32:33]
	v_lshl_add_u64 v[18:19], s[94:95], 0, v[18:19]
	v_lshl_add_u64 v[18:19], s[66:67], 2, v[18:19]
	s_lshl_b32 s48, s87, 2
	v_lshl_add_u64 v[18:19], v[18:19], 0, s[48:49]
	s_waitcnt lgkmcnt(0)
	v_add_f32_e32 v16, v16, v17
	global_store_dword v[18:19], v16, off sc1

.LBB0_764:
	v_mul_f32_e32 v12, v12, v12
	v_mul_f32_e32 v8, v8, v8
	v_mul_f32_e32 v0, v0, v0
	v_fmac_f32_e32 v12, v13, v13
	v_fmac_f32_e32 v8, v9, v9
	v_mul_f32_e32 v4, v4, v4
	v_fmac_f32_e32 v0, v1, v1
	v_fmac_f32_e32 v12, v14, v14
	v_fmac_f32_e32 v8, v10, v10
	v_fmac_f32_e32 v4, v5, v5
	v_fmac_f32_e32 v0, v2, v2
	v_and_b32_e32 v2, 64, v197
	v_fmac_f32_e32 v12, v15, v15
	v_fmac_f32_e32 v8, v11, v11
	v_fmac_f32_e32 v4, v6, v6
	v_xor_b32_e32 v1, 16, v197
	v_add_u32_e32 v2, 64, v2
	v_add_f32_e32 v8, v12, v8
	v_fmac_f32_e32 v4, v7, v7
	v_cmp_lt_i32_e32 vcc, v1, v2
	v_add_f32_e32 v4, v8, v4
	v_fmac_f32_e32 v0, v3, v3
	v_cndmask_b32_e32 v1, v197, v1, vcc
	v_add_f32_e32 v0, v4, v0
	v_lshlrev_b32_e32 v1, 2, v1
	ds_bpermute_b32 v1, v1, v0
	s_waitcnt lgkmcnt(0)
	v_add_f32_e32 v0, v0, v1
	v_xor_b32_e32 v1, 32, v197
	v_cmp_lt_i32_e32 vcc, v1, v2
	s_nop 1
	v_cndmask_b32_e32 v1, v197, v1, vcc
	v_lshlrev_b32_e32 v1, 2, v1
	ds_bpermute_b32 v1, v1, v0
	s_and_saveexec_b64 s[10:11], s[6:7]
	s_cbranch_execz .LBB0_766
	v_lshlrev_b64 v[2:3], 6, v[16:17]
	v_lshl_add_u64 v[2:3], s[94:95], 0, v[2:3]
	v_lshl_add_u64 v[2:3], s[66:67], 2, v[2:3]
	s_lshl_b32 s48, s87, 2
	v_lshl_add_u64 v[2:3], v[2:3], 0, s[48:49]
	s_waitcnt lgkmcnt(0)
	v_add_f32_e32 v0, v0, v1
	global_store_dword v[2:3], v0, off sc1

.LBB0_1042:
	v_cvt_f32_u32_e32 v4, v2
	v_sub_u32_e32 v3, 0, v2
	v_rcp_iflag_f32_e32 v4, v4
	s_nop 0
	v_mul_f32_e32 v4, 0x4f7ffffe, v4
	v_cvt_u32_f32_e32 v4, v4
	v_mul_lo_u32 v1, v3, v4
	v_mul_hi_u32 v1, v4, v1
	v_add_u32_e32 v1, v4, v1
	s_waitcnt vmcnt(0)
	v_mov_b32_e32 v5, v165
	v_mul_hi_u32 v1, v5, v1
	v_mul_lo_u32 v3, v1, v2
	v_sub_u32_e32 v3, v5, v3
	v_add_u32_e32 v4, 1, v1
	v_cmp_ge_u32_e32 vcc, v3, v2
	s_nop 1
	v_cndmask_b32_e32 v1, v1, v4, vcc
	v_sub_u32_e32 v4, v3, v2
	v_cndmask_b32_e32 v3, v3, v4, vcc
	v_add_u32_e32 v4, 1, v1
	v_cmp_ge_u32_e32 vcc, v3, v2
	v_add_u32_e32 v3, 1, v5
	s_nop 0
	v_cndmask_b32_e32 v1, v1, v4, vcc
	v_mul_lo_u32 v4, v2, v1
	v_add_u32_e32 v2, v4, v2
	v_cmp_ne_u32_e32 vcc, v3, v2
	s_waitcnt lgkmcnt(0)
	v_mad_u32_u24 v5, v1, v0, v0
	s_add_u32 s10, s90, 0x494e400
	s_addc_u32 s11, s91, 0
	s_cbranch_vccnz .Lgb_poll
	s_mov_b32 s2, 0xc358c
	s_bitcmp1_b32 s2, s86
	s_cbranch_scc1 .Lgb_nowb
	buffer_wbl2 sc1
	s_waitcnt vmcnt(0)
.Lgb_nowb:
	v_mov_b32_e32 v2, 1
	global_atomic_add v159, v2, s[10:11]
